# P5 selected branch: second half-stage reads its LDS fragments before the scalar mask bookkeeping; inactive stages skip both half-stages with one branch
# baseline (speedup 1.0000x reference)
.LBB0_785:
	ds_read_b128 v[182:185], v246 offset:8192
	ds_read_b128 v[178:181], v246 offset:10240
	ds_read_b128 v[186:189], v247 offset:8192
	ds_read_b128 v[174:177], v247 offset:10240
	ds_read_b128 v[158:161], v244 offset:12288
	ds_read_b128 v[162:165], v244 offset:13312
	ds_read_b128 v[166:169], v244 offset:14336
	ds_read_b128 v[170:173], v244 offset:15360
	s_mov_b64 s[50:51], s[86:87]
	s_mov_b64 s[48:49], s[88:89]
	s_mov_b64 s[46:47], s[90:91]
	s_mov_b64 s[42:43], s[92:93]
	s_add_i32 s2, s28, 0xffffff1f
	s_cmp_le_i32 s2, s26
	s_cselect_b64 s[2:3], -1, 0
	v_cndmask_b32_e64 v0, 0, 1, s[2:3]
	s_cmp_eq_u64 s[50:51], 0
	v_cmp_ne_u32_e64 s[44:45], 1, v0
	s_cbranch_scc1 .LBB0_792
	v_cndmask_b32_e64 v190, v194, 0, s[50:51]
	v_cndmask_b32_e64 v191, v194, 0, s[50:51]
	v_cndmask_b32_e64 v192, v194, 0, s[50:51]
	v_cndmask_b32_e64 v193, v194, 0, s[50:51]
	s_nop 0
	s_waitcnt lgkmcnt(7)
	v_mfma_f32_16x16x32_bf16 v[0:3], v[182:185], v[104:107], v[190:193]
	s_and_b64 vcc, exec, s[44:45]
	s_mov_b64 s[64:65], -1
	s_waitcnt lgkmcnt(6)
	v_mfma_f32_16x16x32_bf16 v[4:7], v[178:181], v[104:107], v[190:193]
	s_waitcnt lgkmcnt(5)
	v_mfma_f32_16x16x32_bf16 v[0:3], v[186:189], v[108:111], v[0:3]
	s_waitcnt lgkmcnt(4)
	v_mfma_f32_16x16x32_bf16 v[4:7], v[174:177], v[108:111], v[4:7]
	s_nop 5
	v_exp_f32_e32 v0, v0
	v_exp_f32_e32 v1, v1
	v_exp_f32_e32 v2, v2
	v_exp_f32_e32 v3, v3
	v_exp_f32_e32 v4, v4
	v_exp_f32_e32 v5, v5
	v_exp_f32_e32 v6, v6
	v_exp_f32_e32 v7, v7
	s_cbranch_vccz .LBB0_791

.LBB0_840:
	ds_read_b128 v[182:185], v246 offset:24576
	ds_read_b128 v[178:181], v246 offset:26624
	ds_read_b128 v[186:189], v247 offset:24576
	ds_read_b128 v[174:177], v247 offset:26624
	ds_read_b128 v[158:161], v244 offset:28672
	ds_read_b128 v[162:165], v244 offset:29696
	ds_read_b128 v[166:169], v244 offset:30720
	ds_read_b128 v[170:173], v244 offset:31744
	s_mov_b64 s[50:51], s[86:87]
	s_mov_b64 s[48:49], s[88:89]
	s_mov_b64 s[46:47], s[90:91]
	s_mov_b64 s[42:43], s[92:93]
	s_add_i32 s2, s28, 0xffffff5f
	s_cmp_le_i32 s2, s26
	s_cselect_b64 s[2:3], -1, 0
	v_cndmask_b32_e64 v0, 0, 1, s[2:3]
	s_cmp_eq_u64 s[50:51], 0
	v_cmp_ne_u32_e64 s[44:45], 1, v0
	s_cbranch_scc1 .LBB0_847
	v_cndmask_b32_e64 v190, v194, 0, s[50:51]
	v_cndmask_b32_e64 v191, v194, 0, s[50:51]
	v_cndmask_b32_e64 v192, v194, 0, s[50:51]
	v_cndmask_b32_e64 v193, v194, 0, s[50:51]
	s_nop 0
	s_waitcnt lgkmcnt(7)
	v_mfma_f32_16x16x32_bf16 v[0:3], v[182:185], v[104:107], v[190:193]
	s_and_b64 vcc, exec, s[44:45]
	s_mov_b64 s[40:41], -1
	s_waitcnt lgkmcnt(6)
	v_mfma_f32_16x16x32_bf16 v[4:7], v[178:181], v[104:107], v[190:193]
	s_waitcnt lgkmcnt(5)
	v_mfma_f32_16x16x32_bf16 v[0:3], v[186:189], v[108:111], v[0:3]
	s_waitcnt lgkmcnt(4)
	v_mfma_f32_16x16x32_bf16 v[4:7], v[174:177], v[108:111], v[4:7]
	s_nop 5
	v_exp_f32_e32 v0, v0
	v_exp_f32_e32 v1, v1
	v_exp_f32_e32 v2, v2
	v_exp_f32_e32 v3, v3
	v_exp_f32_e32 v4, v4
	v_exp_f32_e32 v5, v5
	v_exp_f32_e32 v6, v6
	v_exp_f32_e32 v7, v7
	s_cbranch_vccz .LBB0_846

.LB2_785:
	ds_read_b128 v[182:185], v246 offset:40960
	ds_read_b128 v[178:181], v246 offset:43008
	ds_read_b128 v[186:189], v247 offset:40960
	ds_read_b128 v[174:177], v247 offset:43008
	ds_read_b128 v[158:161], v244 offset:45056
	ds_read_b128 v[162:165], v244 offset:46080
	ds_read_b128 v[166:169], v244 offset:47104
	ds_read_b128 v[170:173], v244 offset:48128
	s_mov_b64 s[50:51], s[86:87]
	s_mov_b64 s[48:49], s[88:89]
	s_mov_b64 s[46:47], s[90:91]
	s_mov_b64 s[42:43], s[92:93]
	s_add_i32 s2, s28, 0xffffff1f
	s_cmp_le_i32 s2, s26
	s_cselect_b64 s[2:3], -1, 0
	v_cndmask_b32_e64 v0, 0, 1, s[2:3]
	s_cmp_eq_u64 s[50:51], 0
	v_cmp_ne_u32_e64 s[44:45], 1, v0
	s_cbranch_scc1 .LB2_792
	v_cndmask_b32_e64 v190, v194, 0, s[50:51]
	v_cndmask_b32_e64 v191, v194, 0, s[50:51]
	v_cndmask_b32_e64 v192, v194, 0, s[50:51]
	v_cndmask_b32_e64 v193, v194, 0, s[50:51]
	s_nop 0
	s_waitcnt lgkmcnt(7)
	v_mfma_f32_16x16x32_bf16 v[0:3], v[182:185], v[104:107], v[190:193]
	s_and_b64 vcc, exec, s[44:45]
	s_mov_b64 s[64:65], -1
	s_waitcnt lgkmcnt(6)
	v_mfma_f32_16x16x32_bf16 v[4:7], v[178:181], v[104:107], v[190:193]
	s_waitcnt lgkmcnt(5)
	v_mfma_f32_16x16x32_bf16 v[0:3], v[186:189], v[108:111], v[0:3]
	s_waitcnt lgkmcnt(4)
	v_mfma_f32_16x16x32_bf16 v[4:7], v[174:177], v[108:111], v[4:7]
	s_nop 5
	v_exp_f32_e32 v0, v0
	v_exp_f32_e32 v1, v1
	v_exp_f32_e32 v2, v2
	v_exp_f32_e32 v3, v3
	v_exp_f32_e32 v4, v4
	v_exp_f32_e32 v5, v5
	v_exp_f32_e32 v6, v6
	v_exp_f32_e32 v7, v7
	s_cbranch_vccz .LB2_791

.LB2_840:
	ds_read_b128 v[182:185], v246 offset:57344
	ds_read_b128 v[178:181], v246 offset:59392
	ds_read_b128 v[186:189], v247 offset:57344
	ds_read_b128 v[174:177], v247 offset:59392
	ds_read_b128 v[158:161], v244 offset:61440
	ds_read_b128 v[162:165], v244 offset:62464
	ds_read_b128 v[166:169], v244 offset:63488
	ds_read_b128 v[170:173], v244 offset:64512
	s_mov_b64 s[50:51], s[86:87]
	s_mov_b64 s[48:49], s[88:89]
	s_mov_b64 s[46:47], s[90:91]
	s_mov_b64 s[42:43], s[92:93]
	s_add_i32 s2, s28, 0xffffff5f
	s_cmp_le_i32 s2, s26
	s_cselect_b64 s[2:3], -1, 0
	v_cndmask_b32_e64 v0, 0, 1, s[2:3]
	s_cmp_eq_u64 s[50:51], 0
	v_cmp_ne_u32_e64 s[44:45], 1, v0
	s_cbranch_scc1 .LB2_847
	v_cndmask_b32_e64 v190, v194, 0, s[50:51]
	v_cndmask_b32_e64 v191, v194, 0, s[50:51]
	v_cndmask_b32_e64 v192, v194, 0, s[50:51]
	v_cndmask_b32_e64 v193, v194, 0, s[50:51]
	s_nop 0
	s_waitcnt lgkmcnt(7)
	v_mfma_f32_16x16x32_bf16 v[0:3], v[182:185], v[104:107], v[190:193]
	s_and_b64 vcc, exec, s[44:45]
	s_mov_b64 s[40:41], -1
	s_waitcnt lgkmcnt(6)
	v_mfma_f32_16x16x32_bf16 v[4:7], v[178:181], v[104:107], v[190:193]
	s_waitcnt lgkmcnt(5)
	v_mfma_f32_16x16x32_bf16 v[0:3], v[186:189], v[108:111], v[0:3]
	s_waitcnt lgkmcnt(4)
	v_mfma_f32_16x16x32_bf16 v[4:7], v[174:177], v[108:111], v[4:7]
	s_nop 5
	v_exp_f32_e32 v0, v0
	v_exp_f32_e32 v1, v1
	v_exp_f32_e32 v2, v2
	v_exp_f32_e32 v3, v3
	v_exp_f32_e32 v4, v4
	v_exp_f32_e32 v5, v5
	v_exp_f32_e32 v6, v6
	v_exp_f32_e32 v7, v7
	s_cbranch_vccz .LB2_846
